# P4 epilogue: row statistics loads hoisted (one latency instead of five); kernarg scalar loads issued together
# speedup vs baseline: 1.0796x; 1.0196x over previous
_Z14fwd_megakernel6Params:
	s_mov_b32 s92, s2
	s_load_dwordx8 s[84:91], s[0:1], 0x80
	s_load_dword s2, s[0:1], 0xa0
	s_load_dwordx16 s[56:71], s[0:1], 0x0
	s_load_dwordx16 s[20:35], s[0:1], 0x40
	v_and_b32_e32 v162, 0x3ff, v0
	v_cmp_eq_u32_e64 s[4:5], 0, v162
	s_waitcnt lgkmcnt(0)
	v_writelane_b32 v251, s2, 0
	s_add_u32 s2, s0, 0x98
	s_addc_u32 s3, s1, 0
	v_writelane_b32 v251, s2, 1
	s_nop 1
	v_writelane_b32 v251, s3, 2
	s_mov_b64 s[2:3], exec
	v_writelane_b32 v251, s4, 3
	s_nop 1
	v_writelane_b32 v251, s5, 4
	s_and_b64 s[4:5], s[2:3], s[4:5]
	s_mov_b64 exec, s[4:5]
	s_cbranch_execz .LBB0_2
	v_mov_b32_e32 v2, 0
	v_mov_b32_e32 v3, v2
	v_mov_b32_e32 v4, v2
	v_mov_b32_e32 v5, v2
	v_mov_b32_e32 v1, 0x20000
	ds_write_b128 v1, v[2:5]
.LBB0_2:
	s_or_b64 exec, exec, s[2:3]
	s_add_u32 s2, s86, 0x16ec000
	s_addc_u32 s3, s87, 0
	s_waitcnt lgkmcnt(0)
	s_barrier
	v_writelane_b32 v251, s20, 5
	s_nop 1
	v_writelane_b32 v251, s21, 6
	v_writelane_b32 v251, s22, 7
	v_writelane_b32 v251, s23, 8
	v_writelane_b32 v251, s24, 9
	v_writelane_b32 v251, s25, 10
	v_writelane_b32 v251, s26, 11
	v_writelane_b32 v251, s27, 12
	v_writelane_b32 v251, s28, 13
	v_writelane_b32 v251, s29, 14
	v_writelane_b32 v251, s30, 15
	v_writelane_b32 v251, s31, 16
	v_writelane_b32 v251, s32, 17
	v_writelane_b32 v251, s33, 18
	v_writelane_b32 v251, s34, 19
	v_writelane_b32 v251, s35, 20
	v_writelane_b32 v251, s2, 21
	s_nop 1
	v_writelane_b32 v251, s3, 22
	s_getreg_b32 s2, hwreg(HW_REG_XCC_ID, 0, 4)
	s_and_b32 s2, s2, 15
	v_writelane_b32 v251, s2, 23
	s_mov_b64 s[2:3], exec
	v_readlane_b32 s4, v251, 3
	v_readlane_b32 s5, v251, 4
	s_and_b64 s[4:5], s[2:3], s[4:5]
	s_mov_b64 exec, s[4:5]
	s_cbranch_execz .LBB0_5
	s_mov_b64 s[4:5], exec
	v_mbcnt_lo_u32_b32 v1, s4, 0
	v_mbcnt_hi_u32_b32 v1, s5, v1
	v_cmp_eq_u32_e32 vcc, 0, v1
	s_and_b64 s[6:7], exec, vcc
	s_mov_b64 exec, s[6:7]
	s_cbranch_execz .LBB0_5
	v_readlane_b32 s6, v251, 23
	s_bcnt1_i32_b64 s4, s[4:5]
	s_lshl_b32 s6, s6, 8
	v_mov_b32_e32 v2, s4
	v_readlane_b32 s4, v251, 21
	v_mov_b32_e32 v1, s6
	v_readlane_b32 s5, v251, 22
	s_nop 4
	global_atomic_add v1, v2, s[4:5] offset:1024
.LBB0_5:
	s_or_b64 exec, exec, s[2:3]
	s_add_u32 s82, s86, 0x16ab000
	s_addc_u32 s83, s87, 0
	s_cmp_lt_i32 s88, 1
	s_cselect_b64 s[10:11], -1, 0
	s_waitcnt lgkmcnt(0)
	v_writelane_b32 v251, s56, 24
	s_cmp_gt_i32 s89, 0
	s_cselect_b64 s[0:1], -1, 0
	v_writelane_b32 v251, s57, 25
	v_writelane_b32 v251, s58, 26
	v_writelane_b32 v251, s59, 27
	v_writelane_b32 v251, s60, 28
	v_writelane_b32 v251, s61, 29
	v_writelane_b32 v251, s62, 30
	v_writelane_b32 v251, s63, 31
	v_writelane_b32 v251, s64, 32
	v_writelane_b32 v251, s65, 33
	v_writelane_b32 v251, s66, 34
	v_writelane_b32 v251, s67, 35
	v_writelane_b32 v251, s68, 36
	s_and_b64 s[0:1], s[10:11], s[0:1]
	v_writelane_b32 v251, s69, 37
	s_andn2_b64 vcc, exec, s[0:1]
	v_writelane_b32 v251, s70, 38
	v_writelane_b32 v251, s71, 39
	s_cbranch_vccnz .LBB0_144
	s_cmp_gt_i32 s88, -1
	s_cbranch_scc0 .LBB0_9
	s_branch .Lp0_start

.Lp0_xtail0:
	s_waitcnt vmcnt(4)
	v_cvt_pk_bf16_f32 v80, v16, v17
	v_cvt_pk_bf16_f32 v81, v18, v19
	v_cvt_pk_bf16_f32 v82, v20, v21
	v_cvt_pk_bf16_f32 v83, v22, v23
	v_cvt_pk_bf16_f32 v84, v24, v25
	v_cvt_pk_bf16_f32 v85, v26, v27
	v_cvt_pk_bf16_f32 v86, v28, v29
	v_cvt_pk_bf16_f32 v87, v30, v31
	global_store_dwordx4 v5, v[80:83], s[48:49]
	global_store_dwordx4 v12, v[84:87], s[48:49]
	s_add_u32 s48, s48, 0x4000
	s_addc_u32 s49, s49, 0
	s_waitcnt vmcnt(0)
	v_cvt_pk_bf16_f32 v80, v32, v33
	v_cvt_pk_bf16_f32 v81, v34, v35
	v_cvt_pk_bf16_f32 v82, v36, v37
	v_cvt_pk_bf16_f32 v83, v38, v39
	v_cvt_pk_bf16_f32 v84, v40, v41
	v_cvt_pk_bf16_f32 v85, v42, v43
	v_cvt_pk_bf16_f32 v86, v44, v45
	v_cvt_pk_bf16_f32 v87, v46, v47
	global_store_dwordx4 v5, v[80:83], s[48:49]
	global_store_dwordx4 v12, v[84:87], s[48:49]
	s_add_u32 s48, s48, 0x4000
	s_addc_u32 s49, s49, 0
	s_branch .Lp0_stzero
.Lp0_xtail1:
	s_waitcnt vmcnt(4)
	v_cvt_pk_bf16_f32 v80, v32, v33
	v_cvt_pk_bf16_f32 v81, v34, v35
	v_cvt_pk_bf16_f32 v82, v36, v37
	v_cvt_pk_bf16_f32 v83, v38, v39
	v_cvt_pk_bf16_f32 v84, v40, v41
	v_cvt_pk_bf16_f32 v85, v42, v43
	v_cvt_pk_bf16_f32 v86, v44, v45
	v_cvt_pk_bf16_f32 v87, v46, v47
	global_store_dwordx4 v5, v[80:83], s[48:49]
	global_store_dwordx4 v12, v[84:87], s[48:49]
	s_add_u32 s48, s48, 0x4000
	s_addc_u32 s49, s49, 0
	s_waitcnt vmcnt(0)
	v_cvt_pk_bf16_f32 v80, v48, v49
	v_cvt_pk_bf16_f32 v81, v50, v51
	v_cvt_pk_bf16_f32 v82, v52, v53
	v_cvt_pk_bf16_f32 v83, v54, v55
	v_cvt_pk_bf16_f32 v84, v56, v57
	v_cvt_pk_bf16_f32 v85, v58, v59
	v_cvt_pk_bf16_f32 v86, v60, v61
	v_cvt_pk_bf16_f32 v87, v62, v63
	global_store_dwordx4 v5, v[80:83], s[48:49]
	global_store_dwordx4 v12, v[84:87], s[48:49]
	s_add_u32 s48, s48, 0x4000
	s_addc_u32 s49, s49, 0
	s_branch .Lp0_stzero
.Lp0_xtail2:
	s_waitcnt vmcnt(4)
	v_cvt_pk_bf16_f32 v80, v48, v49
	v_cvt_pk_bf16_f32 v81, v50, v51
	v_cvt_pk_bf16_f32 v82, v52, v53
	v_cvt_pk_bf16_f32 v83, v54, v55
	v_cvt_pk_bf16_f32 v84, v56, v57
	v_cvt_pk_bf16_f32 v85, v58, v59
	v_cvt_pk_bf16_f32 v86, v60, v61
	v_cvt_pk_bf16_f32 v87, v62, v63
	global_store_dwordx4 v5, v[80:83], s[48:49]
	global_store_dwordx4 v12, v[84:87], s[48:49]
	s_add_u32 s48, s48, 0x4000
	s_addc_u32 s49, s49, 0
	s_waitcnt vmcnt(0)
	v_cvt_pk_bf16_f32 v80, v16, v17
	v_cvt_pk_bf16_f32 v81, v18, v19
	v_cvt_pk_bf16_f32 v82, v20, v21
	v_cvt_pk_bf16_f32 v83, v22, v23
	v_cvt_pk_bf16_f32 v84, v24, v25
	v_cvt_pk_bf16_f32 v85, v26, v27
	v_cvt_pk_bf16_f32 v86, v28, v29
	v_cvt_pk_bf16_f32 v87, v30, v31
	global_store_dwordx4 v5, v[80:83], s[48:49]
	global_store_dwordx4 v12, v[84:87], s[48:49]
	s_add_u32 s48, s48, 0x4000
	s_addc_u32 s49, s49, 0
	s_branch .Lp0_stzero

.LBB0_1095:
	v_lshl_or_b32 v122, s68, 8, v184
	v_ashrrev_i32_e32 v123, 31, v122
	v_lshl_add_u32 v201, s67, 8, v182
	v_lshlrev_b64 v[124:125], 2, v[122:123]
	v_lshlrev_b32_e32 v128, 1, v201
	v_or_b32_e32 v122, 16, v122
	v_ashrrev_i32_e32 v129, 31, v128
	v_ashrrev_i32_e32 v123, 31, v122
	v_lshl_add_u64 v[126:127], s[14:15], 0, v[124:125]
	v_lshl_add_u64 v[128:129], v[128:129], 2, s[82:83]
	v_lshlrev_b64 v[122:123], 2, v[122:123]
	global_load_dwordx2 v[202:203], v[128:129], off
	global_load_dwordx2 v[216:217], v[128:129], off offset:256
	global_load_dwordx2 v[218:219], v[128:129], off offset:384
	global_load_dwordx2 v[220:221], v[128:129], off offset:1024
	global_load_dwordx2 v[222:223], v[128:129], off offset:1152
	global_load_dwordx2 v[224:225], v[128:129], off offset:1280
	global_load_dwordx2 v[226:227], v[128:129], off offset:1408
	global_load_dwordx4 v[154:157], v[126:127], off
	global_load_dwordx4 v[146:149], v[126:127], off offset:512
	v_lshl_add_u64 v[126:127], s[14:15], 0, v[122:123]
	global_load_dwordx4 v[138:141], v[126:127], off
	s_nop 0
	global_load_dwordx4 v[126:129], v[126:127], off offset:512
	v_lshl_add_u64 v[124:125], s[18:19], 0, v[124:125]
	v_lshl_add_u64 v[122:123], s[18:19], 0, v[122:123]
	global_load_dwordx4 v[158:161], v[124:125], off
	global_load_dwordx4 v[150:153], v[124:125], off offset:512
	global_load_dwordx4 v[142:145], v[122:123], off
	s_nop 0
	global_load_dwordx4 v[122:125], v[122:123], off offset:512
	v_readlane_b32 s0, v251, 40
	v_lshl_or_b32 v178, s68, 7, v184
	v_readlane_b32 s1, v251, 41
	v_or_b32_e32 v210, 16, v201
	v_ashrrev_i32_e32 v179, 31, v178
	v_mov_b64_e32 v[176:177], s[0:1]
	v_lshlrev_b32_e32 v206, 1, v210
	v_mad_i64_i32 v[204:205], s[0:1], v201, s64, v[176:177]
	v_lshlrev_b64 v[178:179], 1, v[178:179]
	v_ashrrev_i32_e32 v207, 31, v206
	v_lshl_add_u64 v[204:205], v[204:205], 0, v[178:179]
	v_lshl_add_u64 v[206:207], v[206:207], 2, s[82:83]
	global_load_dwordx2 v[206:207], v[206:207], off
	s_mov_b32 s68, s65
	s_mov_b32 s67, s66
	s_mov_b64 s[26:27], s[54:55]
	s_mov_b64 s[28:29], s[8:9]
	s_waitcnt vmcnt(0)
	v_pk_mul_f32 v[202:203], v[202:203], s[46:47] op_sel_hi:[1,0]
	s_nop 0
	v_fma_f32 v211, -v202, v202, v203
	v_xor_b32_e32 v157, 0x80000000, v157
	v_pk_fma_f32 v[208:209], v[138:139], v[202:203], v[118:119] op_sel_hi:[1,0,1] neg_lo:[1,0,0] neg_hi:[1,0,0]
	v_xor_b32_e32 v119, 0x80000000, v141
	v_xor_b32_e32 v118, 0x80000000, v140
	v_pk_fma_f32 v[140:141], v[126:127], v[202:203], v[114:115] op_sel_hi:[1,0,1] neg_lo:[1,0,0] neg_hi:[1,0,0]
	v_add_f32_e32 v114, 0x3727c5ac, v211
	v_xor_b32_e32 v115, 0x80000000, v129
	v_mul_f32_e32 v129, 0x4b800000, v114
	v_cmp_gt_f32_e32 vcc, s63, v114
	v_xor_b32_e32 v156, 0x80000000, v156
	v_xor_b32_e32 v149, 0x80000000, v149
	v_cndmask_b32_e32 v114, v114, v129, vcc
	v_rsq_f32_e32 v129, v114
	v_xor_b32_e32 v114, 0x80000000, v128
	v_xor_b32_e32 v148, 0x80000000, v148
	v_pk_fma_f32 v[134:135], v[154:155], v[202:203], v[134:135] op_sel_hi:[1,0,1] neg_lo:[1,0,0] neg_hi:[1,0,0]
	v_mul_f32_e32 v128, 0x45800000, v129
	v_cndmask_b32_e32 v128, v129, v128, vcc
	v_pk_fma_f32 v[136:137], v[156:157], v[202:203], v[136:137] op_sel_hi:[1,0,1]
	v_pk_fma_f32 v[130:131], v[146:147], v[202:203], v[130:131] op_sel_hi:[1,0,1] neg_lo:[1,0,0] neg_hi:[1,0,0]
	v_pk_fma_f32 v[132:133], v[148:149], v[202:203], v[132:133] op_sel_hi:[1,0,1]
	v_pk_fma_f32 v[120:121], v[118:119], v[202:203], v[120:121] op_sel_hi:[1,0,1]
	v_pk_fma_f32 v[116:117], v[114:115], v[202:203], v[116:117] op_sel_hi:[1,0,1]
	v_pk_fma_f32 v[134:135], v[134:135], v[128:129], v[158:159] op_sel_hi:[1,0,1]
	v_pk_fma_f32 v[136:137], v[136:137], v[128:129], v[160:161] op_sel_hi:[1,0,1]
	v_pk_fma_f32 v[132:133], v[132:133], v[128:129], v[152:153] op_sel_hi:[1,0,1]
	v_pk_fma_f32 v[130:131], v[130:131], v[128:129], v[150:151] op_sel_hi:[1,0,1]
	v_pk_fma_f32 v[120:121], v[120:121], v[128:129], v[144:145] op_sel_hi:[1,0,1]
	v_pk_fma_f32 v[202:203], v[208:209], v[128:129], v[142:143] op_sel_hi:[1,0,1]
	v_pk_fma_f32 v[116:117], v[116:117], v[128:129], v[124:125] op_sel_hi:[1,0,1]
	v_pk_fma_f32 v[128:129], v[140:141], v[128:129], v[122:123] op_sel_hi:[1,0,1]
	v_mul_f32_e32 v140, 0xbfb8aa3b, v134
	v_mul_f32_e32 v141, 0xbfb8aa3b, v135
	v_exp_f32_e32 v140, v140
	v_mul_f32_e32 v208, 0xbfb8aa3b, v136
	v_mul_f32_e32 v209, 0xbfb8aa3b, v137
	v_exp_f32_e32 v141, v141
	v_exp_f32_e32 v208, v208
	v_exp_f32_e32 v209, v209
	v_add_f32_e32 v140, 1.0, v140
	v_add_f32_e32 v141, 1.0, v141
	v_rcp_f32_e32 v140, v140
	v_add_f32_e32 v208, 1.0, v208
	v_add_f32_e32 v209, 1.0, v209
	v_rcp_f32_e32 v141, v141
	v_mul_f32_e32 v213, 0xbfb8aa3b, v120
	v_rcp_f32_e32 v208, v208
	v_rcp_f32_e32 v209, v209
	v_mul_f32_e32 v211, 0xbfb8aa3b, v202
	v_mul_f32_e32 v212, 0xbfb8aa3b, v203
	v_mul_f32_e32 v214, 0xbfb8aa3b, v121
	v_exp_f32_e32 v213, v213
	v_exp_f32_e32 v211, v211
	v_exp_f32_e32 v212, v212
	v_exp_f32_e32 v214, v214
	v_mul_f32_e32 v134, v134, v140
	v_mul_f32_e32 v135, v135, v141
	v_mul_f32_e32 v130, v130, v134
	v_mul_f32_e32 v136, v136, v208
	v_mul_f32_e32 v137, v137, v209
	v_mul_f32_e32 v131, v131, v135
	v_cvt_pk_bf16_f32 v130, v130, v131
	v_mul_f32_e32 v132, v132, v136
	v_mul_f32_e32 v133, v133, v137
	v_cvt_pk_bf16_f32 v131, v132, v133
	global_store_dwordx2 v[204:205], v[130:131], off
	v_add_f32_e32 v130, 1.0, v213
	v_add_f32_e32 v211, 1.0, v211
	v_add_f32_e32 v212, 1.0, v212
	v_rcp_f32_e32 v130, v130
	v_add_f32_e32 v131, 1.0, v214
	v_rcp_f32_e32 v211, v211
	v_rcp_f32_e32 v212, v212
	v_rcp_f32_e32 v131, v131
	v_mul_f32_e32 v120, v120, v130
	v_mul_f32_e32 v140, v202, v211
	v_mul_f32_e32 v141, v203, v212
	v_mul_f32_e32 v120, v116, v120
	v_mul_f32_e32 v116, v121, v131
	v_mul_f32_e32 v128, v128, v140
	v_mul_f32_e32 v129, v129, v141
	v_mul_f32_e32 v117, v117, v116
	v_cvt_pk_bf16_f32 v116, v128, v129
	v_or_b32_e32 v134, 32, v201
	v_cvt_pk_bf16_f32 v117, v120, v117
	global_store_dwordx2 v[204:205], v[116:117], off offset:32
	v_lshlrev_b32_e32 v116, 1, v134
	v_ashrrev_i32_e32 v117, 31, v116
	v_lshl_add_u64 v[116:117], v[116:117], 2, s[82:83]
	v_mov_b32_e32 v116, v216
	v_mov_b32_e32 v117, v217
	v_pk_mul_f32 v[128:129], v[206:207], s[46:47] op_sel_hi:[1,0]
	v_mad_i64_i32 v[120:121], s[0:1], v210, s64, v[176:177]
	v_mov_b32_e32 v131, v128
	v_mov_b32_e32 v133, v129
	v_pk_fma_f32 v[110:111], v[154:155], v[128:129], v[110:111] op_sel_hi:[1,0,1] neg_lo:[1,0,0] neg_hi:[1,0,0]
	v_pk_fma_f32 v[112:113], v[156:157], v[128:129], v[112:113] op_sel_hi:[1,0,1]
	v_pk_fma_f32 v[106:107], v[146:147], v[128:129], v[106:107] op_sel_hi:[1,0,1] neg_lo:[1,0,0] neg_hi:[1,0,0]
	v_pk_fma_f32 v[108:109], v[148:149], v[128:129], v[108:109] op_sel_hi:[1,0,1]
	v_pk_fma_f32 v[102:103], v[138:139], v[128:129], v[102:103] op_sel_hi:[1,0,1] neg_lo:[1,0,0] neg_hi:[1,0,0]
	v_pk_fma_f32 v[104:105], v[118:119], v[128:129], v[104:105] op_sel_hi:[1,0,1]
	v_pk_fma_f32 v[98:99], v[126:127], v[128:129], v[98:99] op_sel_hi:[1,0,1] neg_lo:[1,0,0] neg_hi:[1,0,0]
	v_pk_fma_f32 v[100:101], v[114:115], v[128:129], v[100:101] op_sel_hi:[1,0,1]
	v_lshl_add_u64 v[120:121], v[120:121], 0, v[178:179]
	v_pk_mul_f32 v[116:117], v[116:117], s[46:47] op_sel_hi:[1,0]
	s_nop 0
	v_mov_b32_e32 v130, v116
	v_mov_b32_e32 v132, v117
	v_pk_fma_f32 v[130:131], v[130:131], v[130:131], v[132:133] neg_lo:[1,0,0] neg_hi:[1,0,0]
	v_pk_fma_f32 v[94:95], v[154:155], v[116:117], v[94:95] op_sel_hi:[1,0,1] neg_lo:[1,0,0] neg_hi:[1,0,0]
	v_pk_add_f32 v[130:131], v[130:131], s[52:53] op_sel_hi:[1,0]
	v_pk_fma_f32 v[96:97], v[156:157], v[116:117], v[96:97] op_sel_hi:[1,0,1]
	v_mul_f32_e32 v132, 0x4b800000, v131
	v_cmp_gt_f32_e32 vcc, s63, v131
	v_mul_f32_e32 v133, 0x4b800000, v130
	v_cmp_gt_f32_e64 s[0:1], s63, v130
	v_cndmask_b32_e32 v131, v131, v132, vcc
	v_rsq_f32_e32 v131, v131
	v_cndmask_b32_e64 v130, v130, v133, s[0:1]
	v_rsq_f32_e32 v130, v130
	v_pk_fma_f32 v[90:91], v[146:147], v[116:117], v[90:91] op_sel_hi:[1,0,1] neg_lo:[1,0,0] neg_hi:[1,0,0]
	v_mul_f32_e32 v128, 0x45800000, v131
	v_cndmask_b32_e32 v128, v131, v128, vcc
	v_mul_f32_e32 v129, 0x45800000, v130
	v_pk_fma_f32 v[112:113], v[112:113], v[128:129], v[160:161] op_sel_hi:[1,0,1]
	v_pk_fma_f32 v[104:105], v[104:105], v[128:129], v[144:145] op_sel_hi:[1,0,1]
	v_pk_fma_f32 v[102:103], v[102:103], v[128:129], v[142:143] op_sel_hi:[1,0,1]
	v_pk_fma_f32 v[110:111], v[110:111], v[128:129], v[158:159] op_sel_hi:[1,0,1]
	v_mul_f32_e32 v131, 0xbfb8aa3b, v112
	v_mul_f32_e32 v132, 0xbfb8aa3b, v113
	v_mul_f32_e32 v135, 0xbfb8aa3b, v103
	v_mul_f32_e32 v137, 0xbfb8aa3b, v105
	v_cndmask_b32_e64 v130, v130, v129, s[0:1]
	v_pk_fma_f32 v[108:109], v[108:109], v[128:129], v[152:153] op_sel_hi:[1,0,1]
	v_pk_fma_f32 v[106:107], v[106:107], v[128:129], v[150:151] op_sel_hi:[1,0,1]
	v_pk_fma_f32 v[100:101], v[100:101], v[128:129], v[124:125] op_sel_hi:[1,0,1]
	v_pk_fma_f32 v[98:99], v[98:99], v[128:129], v[122:123] op_sel_hi:[1,0,1]
	v_mul_f32_e32 v128, 0xbfb8aa3b, v110
	v_mul_f32_e32 v129, 0xbfb8aa3b, v111
	v_mul_f32_e32 v133, 0xbfb8aa3b, v102
	v_mul_f32_e32 v136, 0xbfb8aa3b, v104
	v_exp_f32_e32 v131, v131
	v_exp_f32_e32 v132, v132
	v_exp_f32_e32 v135, v135
	v_exp_f32_e32 v137, v137
	v_exp_f32_e32 v128, v128
	v_exp_f32_e32 v129, v129
	v_exp_f32_e32 v133, v133
	v_exp_f32_e32 v136, v136
	v_add_f32_e32 v131, 1.0, v131
	v_add_f32_e32 v132, 1.0, v132
	v_add_f32_e32 v135, 1.0, v135
	v_add_f32_e32 v137, 1.0, v137
	v_add_f32_e32 v128, 1.0, v128
	v_add_f32_e32 v129, 1.0, v129
	v_add_f32_e32 v133, 1.0, v133
	v_add_f32_e32 v136, 1.0, v136
	v_rcp_f32_e32 v131, v131
	v_rcp_f32_e32 v132, v132
	v_rcp_f32_e32 v135, v135
	v_rcp_f32_e32 v137, v137
	v_rcp_f32_e32 v128, v128
	v_rcp_f32_e32 v129, v129
	v_rcp_f32_e32 v133, v133
	v_rcp_f32_e32 v136, v136
	v_mul_f32_e32 v112, v112, v131
	v_mul_f32_e32 v113, v113, v132
	v_mul_f32_e32 v103, v103, v135
	v_mul_f32_e32 v105, v105, v137
	v_mul_f32_e32 v110, v110, v128
	v_mul_f32_e32 v111, v111, v129
	v_mul_f32_e32 v102, v102, v133
	v_mul_f32_e32 v104, v104, v136
	v_mul_f32_e32 v108, v108, v112
	v_mul_f32_e32 v109, v109, v113
	v_mul_f32_e32 v103, v99, v103
	v_mul_f32_e32 v101, v101, v105
	v_cvt_pk_bf16_f32 v99, v108, v109
	v_pk_fma_f32 v[94:95], v[94:95], v[130:131], v[158:159] op_sel_hi:[1,0,1]
	v_mul_f32_e32 v106, v106, v110
	v_mul_f32_e32 v107, v107, v111
	v_mul_f32_e32 v102, v98, v102
	v_mul_f32_e32 v100, v100, v104
	v_cvt_pk_bf16_f32 v98, v106, v107
	global_store_dwordx2 v[120:121], v[98:99], off
	v_cvt_pk_bf16_f32 v99, v100, v101
	v_mul_f32_e32 v101, 0xbfb8aa3b, v94
	v_exp_f32_e32 v101, v101
	v_cvt_pk_bf16_f32 v98, v102, v103
	v_mul_f32_e32 v102, 0xbfb8aa3b, v95
	v_exp_f32_e32 v102, v102
	v_add_f32_e32 v101, 1.0, v101
	v_rcp_f32_e32 v101, v101
	v_pk_fma_f32 v[96:97], v[96:97], v[130:131], v[160:161] op_sel_hi:[1,0,1]
	v_pk_fma_f32 v[90:91], v[90:91], v[130:131], v[150:151] op_sel_hi:[1,0,1]
	v_pk_fma_f32 v[92:93], v[148:149], v[116:117], v[92:93] op_sel_hi:[1,0,1]
	v_mul_f32_e32 v94, v94, v101
	v_mul_f32_e32 v90, v90, v94
	v_add_f32_e32 v94, 1.0, v102
	v_mul_f32_e32 v101, 0xbfb8aa3b, v96
	v_rcp_f32_e32 v94, v94
	v_exp_f32_e32 v101, v101
	v_mul_f32_e32 v102, 0xbfb8aa3b, v97
	v_exp_f32_e32 v102, v102
	v_mul_f32_e32 v94, v95, v94
	v_add_f32_e32 v95, 1.0, v101
	v_rcp_f32_e32 v95, v95
	v_add_f32_e32 v101, 1.0, v102
	v_rcp_f32_e32 v101, v101
	v_pk_fma_f32 v[92:93], v[92:93], v[130:131], v[152:153] op_sel_hi:[1,0,1]
	v_mul_f32_e32 v91, v91, v94
	v_mul_f32_e32 v94, v96, v95
	v_or_b32_e32 v100, 48, v201
	v_mul_f32_e32 v92, v92, v94
	v_mul_f32_e32 v94, v97, v101
	global_store_dwordx2 v[120:121], v[98:99], off offset:32
	v_lshlrev_b32_e32 v98, 1, v100
	v_mul_f32_e32 v93, v93, v94
	v_ashrrev_i32_e32 v99, 31, v98
	v_cvt_pk_bf16_f32 v90, v90, v91
	v_cvt_pk_bf16_f32 v91, v92, v93
	v_mad_i64_i32 v[92:93], s[0:1], v134, s64, v[176:177]
	v_pk_fma_f32 v[86:87], v[138:139], v[116:117], v[86:87] op_sel_hi:[1,0,1] neg_lo:[1,0,0] neg_hi:[1,0,0]
	v_lshl_add_u64 v[98:99], v[98:99], 2, s[82:83]
	v_lshl_add_u64 v[92:93], v[92:93], 0, v[178:179]
	v_pk_fma_f32 v[86:87], v[86:87], v[130:131], v[142:143] op_sel_hi:[1,0,1]
	v_mov_b32_e32 v98, v218
	v_mov_b32_e32 v99, v219
	v_pk_fma_f32 v[88:89], v[118:119], v[116:117], v[88:89] op_sel_hi:[1,0,1]
	global_store_dwordx2 v[92:93], v[90:91], off
	v_mul_f32_e32 v90, 0xbfb8aa3b, v86
	v_exp_f32_e32 v90, v90
	v_mul_f32_e32 v91, 0xbfb8aa3b, v87
	v_exp_f32_e32 v91, v91
	v_pk_fma_f32 v[82:83], v[126:127], v[116:117], v[82:83] op_sel_hi:[1,0,1] neg_lo:[1,0,0] neg_hi:[1,0,0]
	v_add_f32_e32 v90, 1.0, v90
	v_rcp_f32_e32 v90, v90
	v_pk_fma_f32 v[88:89], v[88:89], v[130:131], v[144:145] op_sel_hi:[1,0,1]
	v_pk_fma_f32 v[82:83], v[82:83], v[130:131], v[122:123] op_sel_hi:[1,0,1]
	v_pk_fma_f32 v[84:85], v[114:115], v[116:117], v[84:85] op_sel_hi:[1,0,1]
	v_mul_f32_e32 v86, v86, v90
	v_mul_f32_e32 v82, v82, v86
	v_add_f32_e32 v86, 1.0, v91
	v_mul_f32_e32 v90, 0xbfb8aa3b, v88
	v_rcp_f32_e32 v86, v86
	v_exp_f32_e32 v90, v90
	v_mul_f32_e32 v91, 0xbfb8aa3b, v89
	v_exp_f32_e32 v91, v91
	v_mul_f32_e32 v86, v87, v86
	v_add_f32_e32 v87, 1.0, v90
	v_rcp_f32_e32 v87, v87
	v_add_f32_e32 v90, 1.0, v91
	v_rcp_f32_e32 v90, v90
	v_pk_fma_f32 v[84:85], v[84:85], v[130:131], v[124:125] op_sel_hi:[1,0,1]
	v_mul_f32_e32 v83, v83, v86
	v_mul_f32_e32 v86, v88, v87
	v_mul_f32_e32 v84, v84, v86
	v_mul_f32_e32 v86, v89, v90
	v_cvt_pk_bf16_f32 v82, v82, v83
	v_add_u32_e32 v90, 0x80, v201
	v_mul_f32_e32 v85, v85, v86
	v_cvt_pk_bf16_f32 v83, v84, v85
	global_store_dwordx2 v[92:93], v[82:83], off offset:32
	v_lshlrev_b32_e32 v82, 1, v90
	v_ashrrev_i32_e32 v83, 31, v82
	v_lshl_add_u64 v[82:83], v[82:83], 2, s[82:83]
	v_mov_b32_e32 v82, v220
	v_mov_b32_e32 v83, v221
	v_pk_mul_f32 v[84:85], v[98:99], s[46:47] op_sel_hi:[1,0]
	s_nop 0
	v_mov_b32_e32 v87, v84
	v_mov_b32_e32 v89, v85
	v_pk_fma_f32 v[78:79], v[154:155], v[84:85], v[78:79] op_sel_hi:[1,0,1] neg_lo:[1,0,0] neg_hi:[1,0,0]
	v_pk_fma_f32 v[80:81], v[156:157], v[84:85], v[80:81] op_sel_hi:[1,0,1]
	v_pk_fma_f32 v[76:77], v[148:149], v[84:85], v[76:77] op_sel_hi:[1,0,1]
	v_pk_fma_f32 v[74:75], v[146:147], v[84:85], v[74:75] op_sel_hi:[1,0,1] neg_lo:[1,0,0] neg_hi:[1,0,0]
	v_pk_fma_f32 v[70:71], v[138:139], v[84:85], v[70:71] op_sel_hi:[1,0,1] neg_lo:[1,0,0] neg_hi:[1,0,0]
	v_pk_fma_f32 v[72:73], v[118:119], v[84:85], v[72:73] op_sel_hi:[1,0,1]
	v_pk_fma_f32 v[66:67], v[126:127], v[84:85], v[66:67] op_sel_hi:[1,0,1] neg_lo:[1,0,0] neg_hi:[1,0,0]
	v_pk_fma_f32 v[68:69], v[114:115], v[84:85], v[68:69] op_sel_hi:[1,0,1]
	v_pk_mul_f32 v[82:83], v[82:83], s[46:47] op_sel_hi:[1,0]
	s_nop 0
	v_mov_b32_e32 v86, v82
	v_mov_b32_e32 v88, v83
	v_pk_fma_f32 v[86:87], v[86:87], v[86:87], v[88:89] neg_lo:[1,0,0] neg_hi:[1,0,0]
	v_pk_fma_f32 v[62:63], v[154:155], v[82:83], v[62:63] op_sel_hi:[1,0,1] neg_lo:[1,0,0] neg_hi:[1,0,0]
	v_pk_add_f32 v[86:87], v[86:87], s[52:53] op_sel_hi:[1,0]
	v_pk_fma_f32 v[64:65], v[156:157], v[82:83], v[64:65] op_sel_hi:[1,0,1]
	v_mul_f32_e32 v88, 0x4b800000, v87
	v_cmp_gt_f32_e32 vcc, s63, v87
	v_cmp_gt_f32_e64 s[0:1], s63, v86
	v_pk_fma_f32 v[58:59], v[146:147], v[82:83], v[58:59] op_sel_hi:[1,0,1] neg_lo:[1,0,0] neg_hi:[1,0,0]
	v_cndmask_b32_e32 v87, v87, v88, vcc
	v_mul_f32_e32 v88, 0x4b800000, v86
	v_rsq_f32_e32 v87, v87
	v_cndmask_b32_e64 v86, v86, v88, s[0:1]
	v_rsq_f32_e32 v88, v86
	v_pk_fma_f32 v[60:61], v[148:149], v[82:83], v[60:61] op_sel_hi:[1,0,1]
	v_mul_f32_e32 v86, 0x45800000, v87
	v_cndmask_b32_e32 v86, v87, v86, vcc
	v_mul_f32_e32 v87, 0x45800000, v88
	v_pk_fma_f32 v[78:79], v[78:79], v[86:87], v[158:159] op_sel_hi:[1,0,1]
	v_cndmask_b32_e64 v88, v88, v87, s[0:1]
	v_pk_fma_f32 v[80:81], v[80:81], v[86:87], v[160:161] op_sel_hi:[1,0,1]
	v_mul_f32_e32 v87, 0xbfb8aa3b, v78
	v_exp_f32_e32 v87, v87
	v_mul_f32_e32 v89, 0xbfb8aa3b, v79
	v_exp_f32_e32 v89, v89
	v_pk_fma_f32 v[54:55], v[138:139], v[82:83], v[54:55] op_sel_hi:[1,0,1] neg_lo:[1,0,0] neg_hi:[1,0,0]
	v_pk_fma_f32 v[76:77], v[76:77], v[86:87], v[152:153] op_sel_hi:[1,0,1]
	v_add_f32_e32 v87, 1.0, v87
	v_rcp_f32_e32 v87, v87
	v_pk_fma_f32 v[56:57], v[118:119], v[82:83], v[56:57] op_sel_hi:[1,0,1]
	v_pk_fma_f32 v[50:51], v[126:127], v[82:83], v[50:51] op_sel_hi:[1,0,1] neg_lo:[1,0,0] neg_hi:[1,0,0]
	v_pk_fma_f32 v[52:53], v[114:115], v[82:83], v[52:53] op_sel_hi:[1,0,1]
	v_pk_fma_f32 v[74:75], v[74:75], v[86:87], v[150:151] op_sel_hi:[1,0,1]
	v_mul_f32_e32 v78, v78, v87
	v_mul_f32_e32 v74, v74, v78
	v_add_f32_e32 v78, 1.0, v89
	v_mul_f32_e32 v87, 0xbfb8aa3b, v80
	v_rcp_f32_e32 v78, v78
	v_exp_f32_e32 v87, v87
	v_mul_f32_e32 v89, 0xbfb8aa3b, v81
	v_exp_f32_e32 v89, v89
	v_mul_f32_e32 v78, v79, v78
	v_add_f32_e32 v79, 1.0, v87
	v_rcp_f32_e32 v79, v79
	v_add_f32_e32 v87, 1.0, v89
	v_rcp_f32_e32 v87, v87
	v_mul_f32_e32 v75, v75, v78
	v_mul_f32_e32 v78, v80, v79
	v_mul_f32_e32 v76, v76, v78
	v_mul_f32_e32 v78, v81, v87
	v_mul_f32_e32 v77, v77, v78
	v_cvt_pk_bf16_f32 v74, v74, v75
	v_cvt_pk_bf16_f32 v75, v76, v77
	v_mad_i64_i32 v[76:77], s[0:1], v100, s64, v[176:177]
	v_lshl_add_u64 v[76:77], v[76:77], 0, v[178:179]
	v_pk_fma_f32 v[70:71], v[70:71], v[86:87], v[142:143] op_sel_hi:[1,0,1]
	global_store_dwordx2 v[76:77], v[74:75], off
	v_mul_f32_e32 v74, 0xbfb8aa3b, v70
	v_exp_f32_e32 v74, v74
	v_mul_f32_e32 v75, 0xbfb8aa3b, v71
	v_exp_f32_e32 v75, v75
	v_pk_fma_f32 v[72:73], v[72:73], v[86:87], v[144:145] op_sel_hi:[1,0,1]
	v_add_f32_e32 v74, 1.0, v74
	v_rcp_f32_e32 v74, v74
	v_pk_fma_f32 v[66:67], v[66:67], v[86:87], v[122:123] op_sel_hi:[1,0,1]
	v_pk_fma_f32 v[68:69], v[68:69], v[86:87], v[124:125] op_sel_hi:[1,0,1]
	v_pk_fma_f32 v[62:63], v[62:63], v[88:89], v[158:159] op_sel_hi:[1,0,1]
	v_mul_f32_e32 v70, v70, v74
	v_mul_f32_e32 v66, v66, v70
	v_add_f32_e32 v70, 1.0, v75
	v_mul_f32_e32 v74, 0xbfb8aa3b, v72
	v_rcp_f32_e32 v70, v70
	v_exp_f32_e32 v74, v74
	v_mul_f32_e32 v75, 0xbfb8aa3b, v73
	v_exp_f32_e32 v75, v75
	v_mul_f32_e32 v70, v71, v70
	v_add_f32_e32 v71, 1.0, v74
	v_rcp_f32_e32 v71, v71
	v_add_f32_e32 v74, 1.0, v75
	v_rcp_f32_e32 v74, v74
	v_mul_f32_e32 v67, v67, v70
	v_mul_f32_e32 v70, v72, v71
	v_mul_f32_e32 v68, v68, v70
	v_mul_f32_e32 v70, v73, v74
	v_mul_f32_e32 v69, v69, v70
	v_cvt_pk_bf16_f32 v66, v66, v67
	v_cvt_pk_bf16_f32 v67, v68, v69
	v_mul_f32_e32 v69, 0xbfb8aa3b, v62
	v_exp_f32_e32 v69, v69
	v_mul_f32_e32 v70, 0xbfb8aa3b, v63
	v_exp_f32_e32 v70, v70
	v_pk_fma_f32 v[64:65], v[64:65], v[88:89], v[160:161] op_sel_hi:[1,0,1]
	v_add_f32_e32 v69, 1.0, v69
	v_rcp_f32_e32 v69, v69
	v_pk_fma_f32 v[58:59], v[58:59], v[88:89], v[150:151] op_sel_hi:[1,0,1]
	v_pk_fma_f32 v[60:61], v[60:61], v[88:89], v[152:153] op_sel_hi:[1,0,1]
	v_add_u32_e32 v68, 0x90, v201
	v_mul_f32_e32 v62, v62, v69
	v_mul_f32_e32 v58, v58, v62
	v_add_f32_e32 v62, 1.0, v70
	v_mul_f32_e32 v69, 0xbfb8aa3b, v64
	v_rcp_f32_e32 v62, v62
	v_exp_f32_e32 v69, v69
	v_mul_f32_e32 v70, 0xbfb8aa3b, v65
	v_exp_f32_e32 v70, v70
	v_mul_f32_e32 v62, v63, v62
	v_add_f32_e32 v63, 1.0, v69
	v_rcp_f32_e32 v63, v63
	v_add_f32_e32 v69, 1.0, v70
	v_rcp_f32_e32 v69, v69
	v_mul_f32_e32 v59, v59, v62
	v_mul_f32_e32 v62, v64, v63
	v_mul_f32_e32 v60, v60, v62
	v_mul_f32_e32 v62, v65, v69
	global_store_dwordx2 v[76:77], v[66:67], off offset:32
	v_lshlrev_b32_e32 v66, 1, v68
	v_mul_f32_e32 v61, v61, v62
	v_ashrrev_i32_e32 v67, 31, v66
	v_cvt_pk_bf16_f32 v58, v58, v59
	v_cvt_pk_bf16_f32 v59, v60, v61
	v_mad_i64_i32 v[60:61], s[0:1], v90, s64, v[176:177]
	v_lshl_add_u64 v[66:67], v[66:67], 2, s[82:83]
	v_lshl_add_u64 v[60:61], v[60:61], 0, v[178:179]
	v_pk_fma_f32 v[54:55], v[54:55], v[88:89], v[142:143] op_sel_hi:[1,0,1]
	v_mov_b32_e32 v66, v222
	v_mov_b32_e32 v67, v223
	v_pk_fma_f32 v[56:57], v[56:57], v[88:89], v[144:145] op_sel_hi:[1,0,1]
	global_store_dwordx2 v[60:61], v[58:59], off
	v_mul_f32_e32 v58, 0xbfb8aa3b, v54
	v_exp_f32_e32 v58, v58
	v_mul_f32_e32 v59, 0xbfb8aa3b, v55
	v_exp_f32_e32 v59, v59
	v_pk_fma_f32 v[50:51], v[50:51], v[88:89], v[122:123] op_sel_hi:[1,0,1]
	v_add_f32_e32 v58, 1.0, v58
	v_rcp_f32_e32 v58, v58
	v_pk_fma_f32 v[52:53], v[52:53], v[88:89], v[124:125] op_sel_hi:[1,0,1]
	v_mul_f32_e32 v54, v54, v58
	v_mul_f32_e32 v50, v50, v54
	v_add_f32_e32 v54, 1.0, v59
	v_mul_f32_e32 v58, 0xbfb8aa3b, v56
	v_rcp_f32_e32 v54, v54
	v_exp_f32_e32 v58, v58
	v_mul_f32_e32 v59, 0xbfb8aa3b, v57
	v_exp_f32_e32 v59, v59
	v_mul_f32_e32 v54, v55, v54
	v_add_f32_e32 v55, 1.0, v58
	v_rcp_f32_e32 v55, v55
	v_add_f32_e32 v58, 1.0, v59
	v_rcp_f32_e32 v58, v58
	v_mul_f32_e32 v51, v51, v54
	v_mul_f32_e32 v54, v56, v55
	v_mul_f32_e32 v52, v52, v54
	v_mul_f32_e32 v54, v57, v58
	v_cvt_pk_bf16_f32 v50, v50, v51
	v_add_u32_e32 v58, 0xa0, v201
	v_mul_f32_e32 v53, v53, v54
	v_cvt_pk_bf16_f32 v51, v52, v53
	global_store_dwordx2 v[60:61], v[50:51], off offset:32
	v_lshlrev_b32_e32 v50, 1, v58
	v_ashrrev_i32_e32 v51, 31, v50
	v_lshl_add_u64 v[50:51], v[50:51], 2, s[82:83]
	v_mov_b32_e32 v50, v224
	v_mov_b32_e32 v51, v225
	v_pk_mul_f32 v[52:53], v[66:67], s[46:47] op_sel_hi:[1,0]
	s_nop 0
	v_mov_b32_e32 v55, v52
	v_mov_b32_e32 v57, v53
	v_pk_fma_f32 v[46:47], v[154:155], v[52:53], v[46:47] op_sel_hi:[1,0,1] neg_lo:[1,0,0] neg_hi:[1,0,0]
	v_pk_fma_f32 v[48:49], v[156:157], v[52:53], v[48:49] op_sel_hi:[1,0,1]
	v_pk_fma_f32 v[44:45], v[148:149], v[52:53], v[44:45] op_sel_hi:[1,0,1]
	v_pk_fma_f32 v[42:43], v[146:147], v[52:53], v[42:43] op_sel_hi:[1,0,1] neg_lo:[1,0,0] neg_hi:[1,0,0]
	v_pk_fma_f32 v[38:39], v[138:139], v[52:53], v[38:39] op_sel_hi:[1,0,1] neg_lo:[1,0,0] neg_hi:[1,0,0]
	v_pk_fma_f32 v[40:41], v[118:119], v[52:53], v[40:41] op_sel_hi:[1,0,1]
	v_pk_fma_f32 v[34:35], v[126:127], v[52:53], v[34:35] op_sel_hi:[1,0,1] neg_lo:[1,0,0] neg_hi:[1,0,0]
	v_pk_fma_f32 v[36:37], v[114:115], v[52:53], v[36:37] op_sel_hi:[1,0,1]
	v_pk_mul_f32 v[50:51], v[50:51], s[46:47] op_sel_hi:[1,0]
	s_nop 0
	v_mov_b32_e32 v54, v50
	v_mov_b32_e32 v56, v51
	v_pk_fma_f32 v[54:55], v[54:55], v[54:55], v[56:57] neg_lo:[1,0,0] neg_hi:[1,0,0]
	v_pk_fma_f32 v[30:31], v[154:155], v[50:51], v[30:31] op_sel_hi:[1,0,1] neg_lo:[1,0,0] neg_hi:[1,0,0]
	v_pk_add_f32 v[54:55], v[54:55], s[52:53] op_sel_hi:[1,0]
	v_pk_fma_f32 v[32:33], v[156:157], v[50:51], v[32:33] op_sel_hi:[1,0,1]
	v_mul_f32_e32 v56, 0x4b800000, v55
	v_cmp_gt_f32_e32 vcc, s63, v55
	v_pk_fma_f32 v[26:27], v[146:147], v[50:51], v[26:27] op_sel_hi:[1,0,1] neg_lo:[1,0,0] neg_hi:[1,0,0]
	v_pk_fma_f32 v[28:29], v[148:149], v[50:51], v[28:29] op_sel_hi:[1,0,1]
	v_cndmask_b32_e32 v55, v55, v56, vcc
	v_rsq_f32_e32 v55, v55
	v_pk_fma_f32 v[22:23], v[138:139], v[50:51], v[22:23] op_sel_hi:[1,0,1] neg_lo:[1,0,0] neg_hi:[1,0,0]
	v_pk_fma_f32 v[24:25], v[118:119], v[50:51], v[24:25] op_sel_hi:[1,0,1]
	v_pk_fma_f32 v[18:19], v[126:127], v[50:51], v[18:19] op_sel_hi:[1,0,1] neg_lo:[1,0,0] neg_hi:[1,0,0]
	v_mul_f32_e32 v56, 0x45800000, v55
	v_cndmask_b32_e32 v56, v55, v56, vcc
	v_pk_fma_f32 v[46:47], v[46:47], v[56:57], v[158:159] op_sel_hi:[1,0,1]
	v_pk_fma_f32 v[48:49], v[48:49], v[56:57], v[160:161] op_sel_hi:[1,0,1]
	v_mul_f32_e32 v55, 0xbfb8aa3b, v46
	v_exp_f32_e32 v55, v55
	v_pk_fma_f32 v[44:45], v[44:45], v[56:57], v[152:153] op_sel_hi:[1,0,1]
	v_mul_f32_e32 v57, 0xbfb8aa3b, v47
	v_exp_f32_e32 v57, v57
	v_add_f32_e32 v55, 1.0, v55
	v_rcp_f32_e32 v55, v55
	v_cmp_gt_f32_e32 vcc, s63, v54
	v_pk_fma_f32 v[42:43], v[42:43], v[56:57], v[150:151] op_sel_hi:[1,0,1]
	v_pk_fma_f32 v[20:21], v[114:115], v[50:51], v[20:21] op_sel_hi:[1,0,1]
	v_mul_f32_e32 v46, v46, v55
	v_mul_f32_e32 v42, v42, v46
	v_add_f32_e32 v46, 1.0, v57
	v_mul_f32_e32 v55, 0xbfb8aa3b, v48
	v_rcp_f32_e32 v46, v46
	v_exp_f32_e32 v55, v55
	v_mul_f32_e32 v57, 0xbfb8aa3b, v49
	v_exp_f32_e32 v57, v57
	v_mul_f32_e32 v46, v47, v46
	v_add_f32_e32 v47, 1.0, v55
	v_rcp_f32_e32 v47, v47
	v_add_f32_e32 v55, 1.0, v57
	v_rcp_f32_e32 v55, v55
	v_mul_f32_e32 v43, v43, v46
	v_mul_f32_e32 v46, v48, v47
	v_mul_f32_e32 v44, v44, v46
	v_mul_f32_e32 v46, v49, v55
	v_mul_f32_e32 v45, v45, v46
	v_cvt_pk_bf16_f32 v42, v42, v43
	v_cvt_pk_bf16_f32 v43, v44, v45
	v_mad_i64_i32 v[44:45], s[0:1], v68, s64, v[176:177]
	v_lshl_add_u64 v[44:45], v[44:45], 0, v[178:179]
	v_pk_fma_f32 v[38:39], v[38:39], v[56:57], v[142:143] op_sel_hi:[1,0,1]
	global_store_dwordx2 v[44:45], v[42:43], off
	v_mul_f32_e32 v42, 0xbfb8aa3b, v38
	v_exp_f32_e32 v42, v42
	v_mul_f32_e32 v43, 0xbfb8aa3b, v39
	v_exp_f32_e32 v43, v43
	v_pk_fma_f32 v[40:41], v[40:41], v[56:57], v[144:145] op_sel_hi:[1,0,1]
	v_add_f32_e32 v42, 1.0, v42
	v_rcp_f32_e32 v42, v42
	v_pk_fma_f32 v[34:35], v[34:35], v[56:57], v[122:123] op_sel_hi:[1,0,1]
	v_pk_fma_f32 v[36:37], v[36:37], v[56:57], v[124:125] op_sel_hi:[1,0,1]
	v_mul_f32_e32 v38, v38, v42
	v_mul_f32_e32 v34, v34, v38
	v_add_f32_e32 v38, 1.0, v43
	v_mul_f32_e32 v42, 0xbfb8aa3b, v40
	v_rcp_f32_e32 v38, v38
	v_exp_f32_e32 v42, v42
	v_mul_f32_e32 v43, 0xbfb8aa3b, v41
	v_exp_f32_e32 v43, v43
	v_mul_f32_e32 v38, v39, v38
	v_add_f32_e32 v39, 1.0, v42
	v_rcp_f32_e32 v39, v39
	v_add_f32_e32 v42, 1.0, v43
	v_rcp_f32_e32 v42, v42
	v_mul_f32_e32 v35, v35, v38
	v_mul_f32_e32 v38, v40, v39
	v_mul_f32_e32 v36, v36, v38
	v_mul_f32_e32 v38, v41, v42
	v_mul_f32_e32 v37, v37, v38
	v_cvt_pk_bf16_f32 v34, v34, v35
	v_cvt_pk_bf16_f32 v35, v36, v37
	v_add_u32_e32 v37, 0xb0, v201
	global_store_dwordx2 v[44:45], v[34:35], off offset:32
	v_lshlrev_b32_e32 v34, 1, v37
	v_ashrrev_i32_e32 v35, 31, v34
	v_lshl_add_u64 v[34:35], v[34:35], 2, s[82:83]
	v_mov_b32_e32 v34, v226
	v_mov_b32_e32 v35, v227
	v_mul_f32_e32 v36, 0x4b800000, v54
	v_cndmask_b32_e32 v36, v54, v36, vcc
	v_rsq_f32_e32 v36, v36
	s_nop 0
	v_mul_f32_e32 v38, 0x45800000, v36
	v_cndmask_b32_e32 v36, v36, v38, vcc
	v_pk_fma_f32 v[30:31], v[30:31], v[36:37], v[158:159] op_sel_hi:[1,0,1]
	v_pk_fma_f32 v[32:33], v[32:33], v[36:37], v[160:161] op_sel_hi:[1,0,1]
	v_mul_f32_e32 v38, 0xbfb8aa3b, v30
	v_exp_f32_e32 v38, v38
	v_mul_f32_e32 v39, 0xbfb8aa3b, v31
	v_exp_f32_e32 v39, v39
	v_pk_fma_f32 v[26:27], v[26:27], v[36:37], v[150:151] op_sel_hi:[1,0,1]
	v_add_f32_e32 v38, 1.0, v38
	v_rcp_f32_e32 v38, v38
	v_pk_fma_f32 v[28:29], v[28:29], v[36:37], v[152:153] op_sel_hi:[1,0,1]
	v_pk_fma_f32 v[22:23], v[22:23], v[36:37], v[142:143] op_sel_hi:[1,0,1]
	v_pk_fma_f32 v[24:25], v[24:25], v[36:37], v[144:145] op_sel_hi:[1,0,1]
	v_mul_f32_e32 v30, v30, v38
	v_mul_f32_e32 v26, v26, v30
	v_add_f32_e32 v30, 1.0, v39
	v_mul_f32_e32 v38, 0xbfb8aa3b, v32
	v_rcp_f32_e32 v30, v30
	v_exp_f32_e32 v38, v38
	v_mul_f32_e32 v39, 0xbfb8aa3b, v33
	v_exp_f32_e32 v39, v39
	v_mul_f32_e32 v30, v31, v30
	v_add_f32_e32 v31, 1.0, v38
	v_rcp_f32_e32 v31, v31
	v_add_f32_e32 v38, 1.0, v39
	v_rcp_f32_e32 v38, v38
	v_mul_f32_e32 v27, v27, v30
	v_mul_f32_e32 v30, v32, v31
	v_mul_f32_e32 v28, v28, v30
	v_mul_f32_e32 v30, v33, v38
	v_mul_f32_e32 v29, v29, v30
	v_mul_f32_e32 v30, 0xbfb8aa3b, v22
	v_exp_f32_e32 v30, v30
	v_mul_f32_e32 v31, 0xbfb8aa3b, v23
	v_exp_f32_e32 v31, v31
	v_pk_fma_f32 v[18:19], v[18:19], v[36:37], v[122:123] op_sel_hi:[1,0,1]
	v_add_f32_e32 v30, 1.0, v30
	v_rcp_f32_e32 v30, v30
	v_pk_fma_f32 v[20:21], v[20:21], v[36:37], v[124:125] op_sel_hi:[1,0,1]
	v_cvt_pk_bf16_f32 v26, v26, v27
	v_cvt_pk_bf16_f32 v27, v28, v29
	v_mul_f32_e32 v22, v22, v30
	v_mul_f32_e32 v18, v18, v22
	v_add_f32_e32 v22, 1.0, v31
	v_mul_f32_e32 v30, 0xbfb8aa3b, v24
	v_rcp_f32_e32 v22, v22
	v_exp_f32_e32 v30, v30
	v_mul_f32_e32 v31, 0xbfb8aa3b, v25
	v_exp_f32_e32 v31, v31
	v_mul_f32_e32 v22, v23, v22
	v_add_f32_e32 v23, 1.0, v30
	v_rcp_f32_e32 v23, v23
	v_add_f32_e32 v30, 1.0, v31
	v_rcp_f32_e32 v30, v30
	v_mul_f32_e32 v19, v19, v22
	v_mul_f32_e32 v22, v24, v23
	v_mul_f32_e32 v22, v20, v22
	v_mul_f32_e32 v20, v25, v30
	v_mul_f32_e32 v23, v21, v20
	v_cvt_pk_bf16_f32 v18, v18, v19
	v_mad_i64_i32 v[28:29], s[0:1], v58, s64, v[176:177]
	v_lshl_add_u64 v[28:29], v[28:29], 0, v[178:179]
	v_pk_mul_f32 v[20:21], v[34:35], s[46:47] op_sel_hi:[1,0]
	s_nop 0
	v_fma_f32 v19, -v20, v20, v21
	v_add_f32_e32 v19, 0x3727c5ac, v19
	v_mul_f32_e32 v24, 0x4b800000, v19
	v_cmp_gt_f32_e32 vcc, s63, v19
	v_pk_fma_f32 v[14:15], v[154:155], v[20:21], v[14:15] op_sel_hi:[1,0,1] neg_lo:[1,0,0] neg_hi:[1,0,0]
	v_pk_fma_f32 v[16:17], v[156:157], v[20:21], v[16:17] op_sel_hi:[1,0,1]
	v_cndmask_b32_e32 v19, v19, v24, vcc
	v_rsq_f32_e32 v24, v19
	v_cvt_pk_bf16_f32 v19, v22, v23
	global_store_dwordx2 v[28:29], v[26:27], off
	global_store_dwordx2 v[28:29], v[18:19], off offset:32
	v_pk_fma_f32 v[12:13], v[148:149], v[20:21], v[12:13] op_sel_hi:[1,0,1]
	v_mul_f32_e32 v18, 0x45800000, v24
	v_cndmask_b32_e32 v18, v24, v18, vcc
	v_pk_fma_f32 v[14:15], v[14:15], v[18:19], v[158:159] op_sel_hi:[1,0,1]
	v_pk_fma_f32 v[16:17], v[16:17], v[18:19], v[160:161] op_sel_hi:[1,0,1]
	v_mul_f32_e32 v19, 0xbfb8aa3b, v14
	v_exp_f32_e32 v19, v19
	v_mul_f32_e32 v22, 0xbfb8aa3b, v15
	v_exp_f32_e32 v22, v22
	v_pk_fma_f32 v[10:11], v[146:147], v[20:21], v[10:11] op_sel_hi:[1,0,1] neg_lo:[1,0,0] neg_hi:[1,0,0]
	v_pk_fma_f32 v[12:13], v[12:13], v[18:19], v[152:153] op_sel_hi:[1,0,1]
	v_add_f32_e32 v19, 1.0, v19
	v_rcp_f32_e32 v19, v19
	v_pk_fma_f32 v[6:7], v[138:139], v[20:21], v[6:7] op_sel_hi:[1,0,1] neg_lo:[1,0,0] neg_hi:[1,0,0]
	v_pk_fma_f32 v[8:9], v[118:119], v[20:21], v[8:9] op_sel_hi:[1,0,1]
	v_pk_fma_f32 v[2:3], v[126:127], v[20:21], v[2:3] op_sel_hi:[1,0,1] neg_lo:[1,0,0] neg_hi:[1,0,0]
	v_pk_fma_f32 v[10:11], v[10:11], v[18:19], v[150:151] op_sel_hi:[1,0,1]
	v_mul_f32_e32 v14, v14, v19
	v_mul_f32_e32 v10, v10, v14
	v_add_f32_e32 v14, 1.0, v22
	v_mul_f32_e32 v19, 0xbfb8aa3b, v16
	v_rcp_f32_e32 v14, v14
	v_exp_f32_e32 v19, v19
	v_mul_f32_e32 v22, 0xbfb8aa3b, v17
	v_exp_f32_e32 v22, v22
	v_mul_f32_e32 v14, v15, v14
	v_add_f32_e32 v15, 1.0, v19
	v_rcp_f32_e32 v15, v15
	v_add_f32_e32 v19, 1.0, v22
	v_rcp_f32_e32 v19, v19
	v_mul_f32_e32 v11, v11, v14
	v_mul_f32_e32 v14, v16, v15
	v_mul_f32_e32 v12, v12, v14
	v_mul_f32_e32 v14, v17, v19
	v_mul_f32_e32 v13, v13, v14
	v_cvt_pk_bf16_f32 v10, v10, v11
	v_cvt_pk_bf16_f32 v11, v12, v13
	v_mad_i64_i32 v[12:13], s[0:1], v37, s64, v[176:177]
	v_lshl_add_u64 v[12:13], v[12:13], 0, v[178:179]
	v_pk_fma_f32 v[6:7], v[6:7], v[18:19], v[142:143] op_sel_hi:[1,0,1]
	global_store_dwordx2 v[12:13], v[10:11], off
	v_mul_f32_e32 v10, 0xbfb8aa3b, v6
	v_exp_f32_e32 v10, v10
	v_mul_f32_e32 v11, 0xbfb8aa3b, v7
	v_exp_f32_e32 v11, v11
	v_pk_fma_f32 v[8:9], v[8:9], v[18:19], v[144:145] op_sel_hi:[1,0,1]
	v_add_f32_e32 v10, 1.0, v10
	v_rcp_f32_e32 v10, v10
	v_pk_fma_f32 v[2:3], v[2:3], v[18:19], v[122:123] op_sel_hi:[1,0,1]
	v_pk_fma_f32 v[4:5], v[114:115], v[20:21], v[4:5] op_sel_hi:[1,0,1]
	s_and_b64 vcc, exec, s[6:7]
	v_mul_f32_e32 v6, v6, v10
	v_mul_f32_e32 v2, v2, v6
	v_add_f32_e32 v6, 1.0, v11
	v_mul_f32_e32 v10, 0xbfb8aa3b, v8
	v_rcp_f32_e32 v6, v6
	v_exp_f32_e32 v10, v10
	v_mul_f32_e32 v11, 0xbfb8aa3b, v9
	v_exp_f32_e32 v11, v11
	v_mul_f32_e32 v6, v7, v6
	v_add_f32_e32 v7, 1.0, v10
	v_rcp_f32_e32 v7, v7
	v_add_f32_e32 v10, 1.0, v11
	v_rcp_f32_e32 v10, v10
	v_pk_fma_f32 v[4:5], v[4:5], v[18:19], v[124:125] op_sel_hi:[1,0,1]
	v_mul_f32_e32 v3, v3, v6
	v_mul_f32_e32 v6, v8, v7
	v_mul_f32_e32 v4, v4, v6
	v_mul_f32_e32 v6, v9, v10
	v_mul_f32_e32 v5, v5, v6
	v_cvt_pk_bf16_f32 v2, v2, v3
	v_cvt_pk_bf16_f32 v3, v4, v5
	global_store_dwordx2 v[12:13], v[2:3], off offset:32
	s_cbranch_vccnz .LBB0_1105
